# grid barrier: the workgroup completing the cross-XCD count releases all eight per-XCD generation words itself; waiting workgroups poll their own XCD's word again (distributed polling, no extra hop)
# baseline (speedup 1.0000x reference)
.LBB0_175:
	s_or_b64 exec, exec, s[8:9]
	s_and_saveexec_b64 s[4:5], s[12:13]
	s_cbranch_execz .LBB0_177
	v_mov_b32_e32 v2, 1
	global_atomic_add v[0:1], v2, off
	v_subrev_co_u32_e32 v0, vcc, 0x1100, v0
	s_nop 1
	v_subbrev_co_u32_e32 v1, vcc, 0, v1, vcc
	global_atomic_add v[0:1], v2, off
	global_atomic_add v[0:1], v2, off offset:256
	global_atomic_add v[0:1], v2, off offset:512
	global_atomic_add v[0:1], v2, off offset:768
	global_atomic_add v[0:1], v2, off offset:1024
	global_atomic_add v[0:1], v2, off offset:1280
	global_atomic_add v[0:1], v2, off offset:1536
	global_atomic_add v[0:1], v2, off offset:1792
.LBB0_177:
	s_or_b64 exec, exec, s[4:5]
	s_mov_b64 s[4:5], exec
	v_mbcnt_lo_u32_b32 v0, s4, 0
	v_mbcnt_hi_u32_b32 v0, s5, v0
	v_cmp_eq_u32_e32 vcc, 0, v0
	s_waitcnt vmcnt(0)
	buffer_inv sc1
	s_and_saveexec_b64 s[8:9], vcc
	s_cbranch_execz .LBB0_179
.LBB0_179:
	s_or_b64 exec, exec, s[8:9]
	s_waitcnt vmcnt(0)

.LBB0_298:
	s_or_b64 exec, exec, s[16:17]
	s_and_saveexec_b64 s[6:7], s[14:15]
	s_cbranch_execz .LBB0_300
	v_mov_b32_e32 v2, 1
	global_atomic_add v[0:1], v2, off
	v_subrev_co_u32_e32 v0, vcc, 0x1100, v0
	s_nop 1
	v_subbrev_co_u32_e32 v1, vcc, 0, v1, vcc
	global_atomic_add v[0:1], v2, off
	global_atomic_add v[0:1], v2, off offset:256
	global_atomic_add v[0:1], v2, off offset:512
	global_atomic_add v[0:1], v2, off offset:768
	global_atomic_add v[0:1], v2, off offset:1024
	global_atomic_add v[0:1], v2, off offset:1280
	global_atomic_add v[0:1], v2, off offset:1536
	global_atomic_add v[0:1], v2, off offset:1792
.LBB0_300:
	s_or_b64 exec, exec, s[6:7]
	s_mov_b64 s[6:7], exec
	v_mbcnt_lo_u32_b32 v0, s6, 0
	v_mbcnt_hi_u32_b32 v0, s7, v0
	v_cmp_eq_u32_e32 vcc, 0, v0
	s_waitcnt vmcnt(0)
	buffer_inv sc1
	s_and_saveexec_b64 s[12:13], vcc
	s_cbranch_execz .LBB0_302
.LBB0_302:
	s_or_b64 exec, exec, s[12:13]
	s_waitcnt vmcnt(0)

.LBB0_549:
	s_or_b64 exec, exec, s[12:13]
	s_and_saveexec_b64 s[6:7], s[14:15]
	s_cbranch_execz .LBB0_551
	v_mov_b32_e32 v2, 1
	global_atomic_add v[0:1], v2, off
	v_subrev_co_u32_e32 v0, vcc, 0x1100, v0
	s_nop 1
	v_subbrev_co_u32_e32 v1, vcc, 0, v1, vcc
	global_atomic_add v[0:1], v2, off
	global_atomic_add v[0:1], v2, off offset:256
	global_atomic_add v[0:1], v2, off offset:512
	global_atomic_add v[0:1], v2, off offset:768
	global_atomic_add v[0:1], v2, off offset:1024
	global_atomic_add v[0:1], v2, off offset:1280
	global_atomic_add v[0:1], v2, off offset:1536
	global_atomic_add v[0:1], v2, off offset:1792
.LBB0_551:
	s_or_b64 exec, exec, s[6:7]
	s_mov_b64 s[6:7], exec
	v_mbcnt_lo_u32_b32 v0, s6, 0
	v_mbcnt_hi_u32_b32 v0, s7, v0
	v_cmp_eq_u32_e32 vcc, 0, v0
	s_waitcnt vmcnt(0)
	buffer_inv sc1
	s_and_saveexec_b64 s[10:11], vcc
	s_cbranch_execz .LBB0_553
.LBB0_553:
	s_or_b64 exec, exec, s[10:11]
	s_waitcnt vmcnt(0)

.LBB0_632:
	s_or_b64 exec, exec, s[6:7]
	s_mov_b64 s[6:7], exec
	v_mbcnt_lo_u32_b32 v0, s6, 0
	v_mbcnt_hi_u32_b32 v0, s7, v0
	v_cmp_eq_u32_e32 vcc, 0, v0
	s_waitcnt vmcnt(0)
	buffer_inv sc1
	s_and_saveexec_b64 s[10:11], vcc
	s_cbranch_execz .LBB0_634
.LBB0_634:
	s_or_b64 exec, exec, s[10:11]
	s_waitcnt vmcnt(0)

.LBB0_711:
	s_or_b64 exec, exec, s[10:11]
	s_and_saveexec_b64 s[4:5], s[12:13]
	s_cbranch_execz .LBB0_713
	v_mov_b32_e32 v2, 1
	global_atomic_add v[0:1], v2, off
	v_subrev_co_u32_e32 v0, vcc, 0x1100, v0
	s_nop 1
	v_subbrev_co_u32_e32 v1, vcc, 0, v1, vcc
	global_atomic_add v[0:1], v2, off
	global_atomic_add v[0:1], v2, off offset:256
	global_atomic_add v[0:1], v2, off offset:512
	global_atomic_add v[0:1], v2, off offset:768
	global_atomic_add v[0:1], v2, off offset:1024
	global_atomic_add v[0:1], v2, off offset:1280
	global_atomic_add v[0:1], v2, off offset:1536
	global_atomic_add v[0:1], v2, off offset:1792
.LBB0_713:
	s_or_b64 exec, exec, s[4:5]
	s_mov_b64 s[4:5], exec
	v_mbcnt_lo_u32_b32 v0, s4, 0
	v_mbcnt_hi_u32_b32 v0, s5, v0
	v_cmp_eq_u32_e32 vcc, 0, v0
	s_waitcnt vmcnt(0)
	buffer_inv sc1
	s_and_saveexec_b64 s[8:9], vcc
	s_cbranch_execz .LBB0_715
.LBB0_715:
	s_or_b64 exec, exec, s[8:9]
	s_waitcnt vmcnt(0)

.LBB0_791:
	s_or_b64 exec, exec, s[4:5]
	s_mov_b64 s[4:5], exec
	v_mbcnt_lo_u32_b32 v0, s4, 0
	v_mbcnt_hi_u32_b32 v0, s5, v0
	v_cmp_eq_u32_e32 vcc, 0, v0
	s_waitcnt vmcnt(0)
	buffer_inv sc1
	s_and_saveexec_b64 s[8:9], vcc
	s_cbranch_execz .LBB0_793
.LBB0_793:
	s_or_b64 exec, exec, s[8:9]
	s_waitcnt vmcnt(0)

.LBB0_866:
	s_or_b64 exec, exec, s[4:5]
	s_mov_b64 s[4:5], exec
	v_mbcnt_lo_u32_b32 v0, s4, 0
	v_mbcnt_hi_u32_b32 v0, s5, v0
	v_cmp_eq_u32_e32 vcc, 0, v0
	s_waitcnt vmcnt(0)
	buffer_inv sc1
	s_and_saveexec_b64 s[8:9], vcc
	s_cbranch_execz .LBB0_868
.LBB0_868:
	s_or_b64 exec, exec, s[8:9]
	s_waitcnt vmcnt(0)

.LBB0_1018:
	s_or_b64 exec, exec, s[24:25]
	s_and_saveexec_b64 s[4:5], s[8:9]
	s_cbranch_execz .LBB0_1020
	v_mov_b32_e32 v2, 1
	global_atomic_add v[0:1], v2, off
	v_subrev_co_u32_e32 v0, vcc, 0x1100, v0
	s_nop 1
	v_subbrev_co_u32_e32 v1, vcc, 0, v1, vcc
	global_atomic_add v[0:1], v2, off
	global_atomic_add v[0:1], v2, off offset:256
	global_atomic_add v[0:1], v2, off offset:512
	global_atomic_add v[0:1], v2, off offset:768
	global_atomic_add v[0:1], v2, off offset:1024
	global_atomic_add v[0:1], v2, off offset:1280
	global_atomic_add v[0:1], v2, off offset:1536
	global_atomic_add v[0:1], v2, off offset:1792
.LBB0_1020:
	s_or_b64 exec, exec, s[4:5]
	s_mov_b64 s[4:5], exec
	v_mbcnt_lo_u32_b32 v0, s4, 0
	v_mbcnt_hi_u32_b32 v0, s5, v0
	v_cmp_eq_u32_e32 vcc, 0, v0
	s_waitcnt vmcnt(0)
	buffer_inv sc1
	s_and_saveexec_b64 s[8:9], vcc
	s_cbranch_execz .LBB0_889
	s_branch .LBB0_889

.LBB0_1260:
	s_getpc_b64 s[98:99]
